# adds the unit-transition grace to the P5 merge GEMM (3 transitions per workgroup)
# speedup vs baseline: 1.0165x; 1.0085x over previous
;     __device__ __forceinline__ void init(int G_, int c_) { so.init(TOK, DM, G_, c_); nt = (so.nwg > c_) ? (so.nwg - c_ + G_ - 1) / G_ : 0; }
; __global__ void __launch_bounds__(512, 2) fwd_megakernel(Args a) {
;     ...
;     if (IN(5)) {
;         static_assert(WS_WB == WS_WA + (size_t)DM * 1024 * 2, "Wa_t and Wb_t are contiguous");
;         pg8::Gemm g_{(const pg8::bf16_t*)YA, (const pg8::bf16_t*)Wa_t, 2 * TOK, 2 * DM, 1024}; MergeOrder S_; S_.init(G, bx);
;         EpiMerge2 E{GAB, GAB + (size_t)TOK * 2048, MERGED};
;         pg8::gemm_phase<EpiMerge2, MergeOrder, true, true>(LG, g_, S_, E);
.LBB0_859:
	s_cmp_lt_i32 s66, 6
	s_cselect_b64 s[2:3], -1, 0
	s_and_b64 s[2:3], s[2:3], s[0:1]
	s_andn2_b64 vcc, exec, s[2:3]
	s_cbranch_vccnz .LBB0_923
	s_mov_b32 s100, 0
	s_cmpk_lt_i32 s77, 0x200
	s_cselect_b64 s[0:1], -1, 0
	s_cmpk_gt_i32 s77, 0x1ff
	s_mov_b32 s28, 0
	s_cbranch_scc1 .LBB0_862
	s_abs_i32 s4, s82
	v_cvt_f32_u32_e32 v0, s4
	s_sub_i32 s5, s82, s77
	s_add_i32 s6, s5, 0x1ff
	s_sub_i32 s5, 0xfffffe01, s5
	v_rcp_iflag_f32_e32 v0, v0
	s_xor_b32 s8, s6, s82
	s_sub_i32 s7, 0, s4
	s_max_i32 s5, s6, s5
	v_mul_f32_e32 v0, 0x4f7ffffe, v0
	v_cvt_u32_f32_e32 v0, v0
	s_ashr_i32 s6, s8, 31
	v_readfirstlane_b32 s8, v0
	s_mul_i32 s7, s7, s8
	s_mul_hi_u32 s7, s8, s7
	s_add_i32 s8, s8, s7
	s_mul_hi_u32 s7, s5, s8
	s_mul_i32 s8, s7, s4
	s_sub_i32 s5, s5, s8
	s_add_i32 s9, s7, 1
	s_sub_i32 s8, s5, s4
	s_cmp_ge_u32 s5, s4
	s_cselect_b32 s7, s9, s7
	s_cselect_b32 s5, s8, s5
	s_add_i32 s8, s7, 1
	s_cmp_ge_u32 s5, s4
	s_cselect_b32 s4, s8, s7
	s_xor_b32 s4, s4, s6
	s_sub_i32 s28, s4, s6

; #define PG8_STAGE(bufoff, gbase, voff) do { _Pragma("unroll") for (int _i = 0; _i < 2; ++_i) \
;         __builtin_amdgcn_global_load_lds((const unsigned*)((const char*)(gbase) + (voff)[_i]), (PG8_LAS unsigned*)(lds + (bufoff) + ldsw + _i * 8192), 16, 0, 0); } while (0)
; #define PG8_LDA(dst, b, h) do { _Pragma("unroll") for (int m = 0; m < 4; ++m) _Pragma("unroll") for (int k = 0; k < 2; ++k) dst[m][k] = *(const PG8_LAS bf16x8*)(lds + PG8_SA(b, h) + aoff + m * 2048 + k * 1024); } while (0)
; #define PG8_LDB(dst, b, h) do { _Pragma("unroll") for (int n = 0; n < 2; ++n) _Pragma("unroll") for (int k = 0; k < 2; ++k) dst[n][k] = *(const PG8_LAS bf16x8*)(lds + PG8_SB(b, h) + boff + n * 2048 + k * 1024); } while (0)
; #define PG8_MMA(ai, bj, At, Bt) do { __builtin_amdgcn_s_setprio(1); _Pragma("unroll") for (int m = 0; m < 4; ++m) _Pragma("unroll") for (int n = 0; n < 2; ++n) _Pragma("unroll") for (int k = 0; k < 2; ++k) \
;         acc[ai][bj][m][n] = __builtin_amdgcn_mfma_f32_16x16x32_bf16(Bt[n][k], At[m][k], acc[ai][bj][m][n], 0, 0, 0); __builtin_amdgcn_s_setprio(0); } while (0)
; #define PG8_WAIT_V(n) asm volatile("s_waitcnt vmcnt(" #n ")" ::: "memory")
; #define PG8_BAR __builtin_amdgcn_s_barrier()
; template <class Epi, class Sched, bool ALIGN_EPI = false, bool SP2 = false>
; __device__ __forceinline__ void gemm_phase(PG8_LAS unsigned char* lds, const Gemm g, const Sched& S, const Epi& E) {
;     ...
;         for (int t = 0; t < nt; t += 2) {
;             const bool last = (t == nt - 2);
;             const char* a1 = cA + (size_t)(t + 1) * kstep;
;             const char* a2 = last ? nA : cA + (size_t)(t + 2) * kstep; const char* b2 = last ? nB : cB + (size_t)(t + 2) * kstep;
;             const char* a3 = a2 + kstep; const char* b3 = b2 + kstep;
;             if (last && has_next) S.a_ready(nxt);
;             if constexpr (SP2) {
;             PG8_LDB(B0, 0, 0); PG8_LDB(B1, 0, 1); PG8_SCHED; PG8_LDA(At, 0, 0); PG8_STAGE(PG8_SA(1, 1), a1 + hstep, voffA);
;             PG8_WAIT_V(8); PG8_WAIT_L(0); PG8_BAR; PG8_MMA(0, 0, At, B0); PG8_MMA(0, 1, At, B1); PG8_BAR; PG8_SCHED;
;             PG8_LDA(At, 0, 1); PG8_STAGE(PG8_SB(0, 0), b2, voffB); PG8_STAGE(PG8_SB(0, 1), b2 + hstep, voffB); PG8_STAGE(PG8_SA(0, 0), a2, voffA);
;             PG8_WAIT_V(8); PG8_WAIT_L(0); PG8_BAR; PG8_MMA(1, 0, At, B0); PG8_MMA(1, 1, At, B1); PG8_BAR; PG8_SCHED;
.LBB0_884:
	ds_read_b128 v[128:131], v224
	ds_read_b128 v[132:135], v224 offset:1024
	ds_read_b128 v[136:139], v224 offset:2048
	ds_read_b128 v[140:143], v224 offset:3072
	ds_read_b128 v[144:147], v225
	ds_read_b128 v[148:151], v225 offset:1024
	ds_read_b128 v[152:155], v225 offset:2048
	ds_read_b128 v[156:159], v225 offset:3072
	s_add_u32 s24, s0, 0xfffc0080
	s_addc_u32 s25, s1, -1
	s_cmp_eq_u32 s46, 12
	s_cselect_b32 s27, s15, s25
	s_cselect_b32 s26, s23, s24
	s_cselect_b32 s25, s13, s45
	s_cselect_b32 s24, s43, s44
	v_lshl_add_u64 v[208:209], s[0:1], 0, v[200:201]
	s_add_i32 m0, s21, 0xc000
	ds_read_b128 v[160:163], v226
	ds_read_b128 v[164:167], v226 offset:1024
	ds_read_b128 v[168:171], v226 offset:2048
	ds_read_b128 v[172:175], v226 offset:3072
	ds_read_b128 v[176:179], v226 offset:4096
	ds_read_b128 v[180:183], v226 offset:5120
	ds_read_b128 v[184:187], v226 offset:6144
	ds_read_b128 v[188:191], v226 offset:7168
	s_cmp_lg_u32 s100, 0
	s_cbranch_scc1 .Lgr_p5_0
	global_load_lds_dwordx4 v[208:209], off
	v_lshl_add_u64 v[208:209], s[0:1], 0, v[202:203]
	s_add_i32 m0, s21, 0xe000
	s_nop 0
	global_load_lds_dwordx4 v[208:209], off
	s_waitcnt vmcnt(8)
.Lgr_p5_0:
	s_waitcnt lgkmcnt(0)
	s_barrier
	s_setprio 1
	s_waitcnt lgkmcnt(0)
	v_mfma_f32_16x16x32_bf16 v[124:127], v[128:131], v[160:163], v[124:127]
	v_mfma_f32_16x16x32_bf16 v[120:123], v[136:139], v[160:163], v[120:123]
	v_mfma_f32_16x16x32_bf16 v[108:111], v[128:131], v[168:171], v[108:111]
	v_mfma_f32_16x16x32_bf16 v[104:107], v[136:139], v[168:171], v[104:107]
	v_mfma_f32_16x16x32_bf16 v[92:95], v[128:131], v[176:179], v[92:95]
	v_mfma_f32_16x16x32_bf16 v[88:91], v[136:139], v[176:179], v[88:91]
	v_mfma_f32_16x16x32_bf16 v[76:79], v[128:131], v[184:187], v[76:79]
	v_mfma_f32_16x16x32_bf16 v[72:75], v[136:139], v[184:187], v[72:75]
	v_mfma_f32_16x16x32_bf16 v[124:127], v[132:135], v[164:167], v[124:127]
	v_mfma_f32_16x16x32_bf16 v[120:123], v[140:143], v[164:167], v[120:123]
	v_mfma_f32_16x16x32_bf16 v[108:111], v[132:135], v[172:175], v[108:111]
	v_mfma_f32_16x16x32_bf16 v[104:107], v[140:143], v[172:175], v[104:107]
	v_mfma_f32_16x16x32_bf16 v[92:95], v[132:135], v[180:183], v[92:95]
	v_mfma_f32_16x16x32_bf16 v[88:91], v[140:143], v[180:183], v[88:91]
	v_mfma_f32_16x16x32_bf16 v[76:79], v[132:135], v[188:191], v[76:79]
	v_mfma_f32_16x16x32_bf16 v[72:75], v[140:143], v[188:191], v[72:75]
	s_setprio 0
	s_setprio 1
	v_mfma_f32_16x16x32_bf16 v[116:119], v[144:147], v[160:163], v[116:119]
	v_mfma_f32_16x16x32_bf16 v[112:115], v[152:155], v[160:163], v[112:115]
	v_mfma_f32_16x16x32_bf16 v[100:103], v[144:147], v[168:171], v[100:103]
	v_mfma_f32_16x16x32_bf16 v[96:99], v[152:155], v[168:171], v[96:99]
	v_mfma_f32_16x16x32_bf16 v[84:87], v[144:147], v[176:179], v[84:87]
	v_mfma_f32_16x16x32_bf16 v[80:83], v[152:155], v[176:179], v[80:83]
	v_mfma_f32_16x16x32_bf16 v[68:71], v[144:147], v[184:187], v[68:71]
	v_mfma_f32_16x16x32_bf16 v[64:67], v[152:155], v[184:187], v[64:67]
	v_mfma_f32_16x16x32_bf16 v[116:119], v[148:151], v[164:167], v[116:119]
	v_mfma_f32_16x16x32_bf16 v[112:115], v[156:159], v[164:167], v[112:115]
	v_mfma_f32_16x16x32_bf16 v[100:103], v[148:151], v[172:175], v[100:103]
	v_mfma_f32_16x16x32_bf16 v[96:99], v[156:159], v[172:175], v[96:99]
	v_mfma_f32_16x16x32_bf16 v[84:87], v[148:151], v[180:183], v[84:87]
	v_mfma_f32_16x16x32_bf16 v[80:83], v[156:159], v[180:183], v[80:83]
	v_mfma_f32_16x16x32_bf16 v[68:71], v[148:151], v[188:191], v[68:71]
	v_mfma_f32_16x16x32_bf16 v[64:67], v[156:159], v[188:191], v[64:67]
	s_setprio 0
	s_barrier
	s_add_i32 s47, s41, s29
	v_lshl_add_u64 v[208:209], s[24:25], 0, v[194:195]
	s_mov_b32 m0, s47
	ds_read_b128 v[160:163], v226 offset:16384
	ds_read_b128 v[164:167], v226 offset:17408
	ds_read_b128 v[168:171], v226 offset:18432
	ds_read_b128 v[172:175], v226 offset:19456
	ds_read_b128 v[176:179], v226 offset:20480
	ds_read_b128 v[180:183], v226 offset:21504
	ds_read_b128 v[184:187], v226 offset:22528
	ds_read_b128 v[188:191], v226 offset:23552
	global_load_lds_dwordx4 v[208:209], off
	s_add_i32 m0, s47, 0x2000
	s_add_u32 s48, s24, 0x40000
	v_lshl_add_u64 v[210:211], s[24:25], 0, v[198:199]
	s_addc_u32 s49, s25, 0
	s_add_i32 s47, s42, s29
	global_load_lds_dwordx4 v[210:211], off
	v_lshl_add_u64 v[212:213], s[48:49], 0, v[194:195]
	s_mov_b32 m0, s47
	v_lshl_add_u64 v[214:215], s[26:27], 0, v[196:197]
	global_load_lds_dwordx4 v[212:213], off
	v_lshl_add_u64 v[212:213], s[48:49], 0, v[198:199]
	s_add_i32 m0, s47, 0x2000
	s_nop 0
	global_load_lds_dwordx4 v[212:213], off
	v_lshl_add_u64 v[212:213], s[26:27], 0, v[192:193]
	s_mov_b32 m0, s21
	s_nop 0
	global_load_lds_dwordx4 v[212:213], off
	s_mov_b32 m0, s30
	s_nop 0
	global_load_lds_dwordx4 v[214:215], off
	s_cmp_lg_u32 s100, 0
	s_cbranch_scc1 .Lgr_p5_1
	s_waitcnt vmcnt(8)
; #define PG8_STAGE(bufoff, gbase, voff) do { _Pragma("unroll") for (int _i = 0; _i < 2; ++_i) \
;         __builtin_amdgcn_global_load_lds((const unsigned*)((const char*)(gbase) + (voff)[_i]), (PG8_LAS unsigned*)(lds + (bufoff) + ldsw + _i * 8192), 16, 0, 0); } while (0)
; #define PG8_LDA(dst, b, h) do { _Pragma("unroll") for (int m = 0; m < 4; ++m) _Pragma("unroll") for (int k = 0; k < 2; ++k) dst[m][k] = *(const PG8_LAS bf16x8*)(lds + PG8_SA(b, h) + aoff + m * 2048 + k * 1024); } while (0)
; #define PG8_LDB(dst, b, h) do { _Pragma("unroll") for (int n = 0; n < 2; ++n) _Pragma("unroll") for (int k = 0; k < 2; ++k) dst[n][k] = *(const PG8_LAS bf16x8*)(lds + PG8_SB(b, h) + boff + n * 2048 + k * 1024); } while (0)
; #define PG8_MMA(ai, bj, At, Bt) do { __builtin_amdgcn_s_setprio(1); _Pragma("unroll") for (int m = 0; m < 4; ++m) _Pragma("unroll") for (int n = 0; n < 2; ++n) _Pragma("unroll") for (int k = 0; k < 2; ++k) \
;         acc[ai][bj][m][n] = __builtin_amdgcn_mfma_f32_16x16x32_bf16(Bt[n][k], At[m][k], acc[ai][bj][m][n], 0, 0, 0); __builtin_amdgcn_s_setprio(0); } while (0)
; #define PG8_WAIT_V(n) asm volatile("s_waitcnt vmcnt(" #n ")" ::: "memory")
; #define PG8_WAIT_L(n) asm volatile("s_waitcnt lgkmcnt(" #n ")" ::: "memory")
; #define PG8_BAR __builtin_amdgcn_s_barrier()
; #define PG8_SCHED __builtin_amdgcn_sched_barrier(0)
; template <class Epi, class Sched, bool ALIGN_EPI = false, bool SP2 = false>
; __device__ __forceinline__ void gemm_phase(PG8_LAS unsigned char* lds, const Gemm g, const Sched& S, const Epi& E) {
;     ...
;             PG8_WAIT_V(8); PG8_WAIT_L(0); PG8_BAR; PG8_MMA(1, 0, At, B0); PG8_MMA(1, 1, At, B1); PG8_BAR; PG8_SCHED;
;             PG8_LDB(B0, 1, 0); PG8_LDB(B1, 1, 1); PG8_SCHED; PG8_LDA(At, 1, 0); PG8_STAGE(PG8_SA(0, 1), a2 + hstep, voffA);
;             PG8_WAIT_V(8); PG8_WAIT_L(0); PG8_BAR; PG8_MMA(0, 0, At, B0); PG8_MMA(0, 1, At, B1); PG8_BAR; PG8_SCHED;
.Lgr_p5_1:
	s_waitcnt lgkmcnt(0)
	s_barrier
	s_setprio 1
	s_waitcnt lgkmcnt(0)
	v_mfma_f32_16x16x32_bf16 v[60:63], v[128:131], v[160:163], v[60:63]
	v_mfma_f32_16x16x32_bf16 v[56:59], v[136:139], v[160:163], v[56:59]
	v_mfma_f32_16x16x32_bf16 v[44:47], v[128:131], v[168:171], v[44:47]
	v_mfma_f32_16x16x32_bf16 v[40:43], v[136:139], v[168:171], v[40:43]
	v_mfma_f32_16x16x32_bf16 v[28:31], v[128:131], v[176:179], v[28:31]
	v_mfma_f32_16x16x32_bf16 v[24:27], v[136:139], v[176:179], v[24:27]
	v_mfma_f32_16x16x32_bf16 v[12:15], v[128:131], v[184:187], v[12:15]
	v_mfma_f32_16x16x32_bf16 v[8:11], v[136:139], v[184:187], v[8:11]
	v_mfma_f32_16x16x32_bf16 v[60:63], v[132:135], v[164:167], v[60:63]
	v_mfma_f32_16x16x32_bf16 v[56:59], v[140:143], v[164:167], v[56:59]
	v_mfma_f32_16x16x32_bf16 v[44:47], v[132:135], v[172:175], v[44:47]
	v_mfma_f32_16x16x32_bf16 v[40:43], v[140:143], v[172:175], v[40:43]
	v_mfma_f32_16x16x32_bf16 v[28:31], v[132:135], v[180:183], v[28:31]
	v_mfma_f32_16x16x32_bf16 v[24:27], v[140:143], v[180:183], v[24:27]
	v_mfma_f32_16x16x32_bf16 v[12:15], v[132:135], v[188:191], v[12:15]
	v_mfma_f32_16x16x32_bf16 v[8:11], v[140:143], v[188:191], v[8:11]
	s_setprio 0
	s_setprio 1
	v_mfma_f32_16x16x32_bf16 v[52:55], v[144:147], v[160:163], v[52:55]
	v_mfma_f32_16x16x32_bf16 v[48:51], v[152:155], v[160:163], v[48:51]
	v_mfma_f32_16x16x32_bf16 v[36:39], v[144:147], v[168:171], v[36:39]
	v_mfma_f32_16x16x32_bf16 v[32:35], v[152:155], v[168:171], v[32:35]
	v_mfma_f32_16x16x32_bf16 v[20:23], v[144:147], v[176:179], v[20:23]
	v_mfma_f32_16x16x32_bf16 v[16:19], v[152:155], v[176:179], v[16:19]
	v_mfma_f32_16x16x32_bf16 v[4:7], v[144:147], v[184:187], v[4:7]
	v_mfma_f32_16x16x32_bf16 v[0:3], v[152:155], v[184:187], v[0:3]
	v_mfma_f32_16x16x32_bf16 v[52:55], v[148:151], v[164:167], v[52:55]
	v_mfma_f32_16x16x32_bf16 v[48:51], v[156:159], v[164:167], v[48:51]
	v_mfma_f32_16x16x32_bf16 v[36:39], v[148:151], v[172:175], v[36:39]
	v_mfma_f32_16x16x32_bf16 v[32:35], v[156:159], v[172:175], v[32:35]
	v_mfma_f32_16x16x32_bf16 v[20:23], v[148:151], v[180:183], v[20:23]
	v_mfma_f32_16x16x32_bf16 v[16:19], v[156:159], v[180:183], v[16:19]
	v_mfma_f32_16x16x32_bf16 v[4:7], v[148:151], v[188:191], v[4:7]
	v_mfma_f32_16x16x32_bf16 v[0:3], v[156:159], v[188:191], v[0:3]
	s_setprio 0
	s_barrier
	s_add_i32 s47, 0, 0x18000
	s_add_i32 s48, 0, 0x1c000
	v_add_u32_e32 v140, s47, v222
	v_add_u32_e32 v156, s48, v222
	ds_read_b128 v[128:131], v140
	ds_read_b128 v[132:135], v140 offset:1024
	ds_read_b128 v[136:139], v140 offset:2048
	ds_read_b128 v[140:143], v140 offset:3072
	ds_read_b128 v[144:147], v156
	ds_read_b128 v[148:151], v156 offset:1024
	ds_read_b128 v[152:155], v156 offset:2048
	ds_read_b128 v[156:159], v156 offset:3072
	s_add_u32 s26, s26, 0x40000
	s_addc_u32 s27, s27, 0
	s_mov_b32 m0, s31
	v_lshl_add_u64 v[216:217], s[26:27], 0, v[192:193]
	ds_read_b128 v[160:163], v226 offset:32768
	ds_read_b128 v[164:167], v226 offset:33792
	ds_read_b128 v[168:171], v226 offset:34816
	ds_read_b128 v[172:175], v226 offset:35840
	ds_read_b128 v[176:179], v226 offset:36864
	ds_read_b128 v[180:183], v226 offset:37888
	ds_read_b128 v[184:187], v226 offset:38912
	ds_read_b128 v[188:191], v226 offset:39936
	global_load_lds_dwordx4 v[216:217], off
	v_lshl_add_u64 v[216:217], s[26:27], 0, v[196:197]
	s_mov_b32 m0, s33
	s_nop 0
	global_load_lds_dwordx4 v[216:217], off
	s_cmp_lg_u32 s100, 0
	s_cbranch_scc1 .Lgr_p5_2
	s_waitcnt vmcnt(8)
.Lgr_p5_2:
	s_waitcnt lgkmcnt(0)
	s_barrier
	s_setprio 1
	s_waitcnt lgkmcnt(0)
	v_mfma_f32_16x16x32_bf16 v[124:127], v[128:131], v[160:163], v[124:127]
	v_mfma_f32_16x16x32_bf16 v[120:123], v[136:139], v[160:163], v[120:123]
	v_mfma_f32_16x16x32_bf16 v[108:111], v[128:131], v[168:171], v[108:111]
	v_mfma_f32_16x16x32_bf16 v[104:107], v[136:139], v[168:171], v[104:107]
	v_mfma_f32_16x16x32_bf16 v[92:95], v[128:131], v[176:179], v[92:95]
	v_mfma_f32_16x16x32_bf16 v[88:91], v[136:139], v[176:179], v[88:91]
	v_mfma_f32_16x16x32_bf16 v[76:79], v[128:131], v[184:187], v[76:79]
	v_mfma_f32_16x16x32_bf16 v[72:75], v[136:139], v[184:187], v[72:75]
	v_mfma_f32_16x16x32_bf16 v[124:127], v[132:135], v[164:167], v[124:127]
	v_mfma_f32_16x16x32_bf16 v[120:123], v[140:143], v[164:167], v[120:123]
	v_mfma_f32_16x16x32_bf16 v[108:111], v[132:135], v[172:175], v[108:111]
	v_mfma_f32_16x16x32_bf16 v[104:107], v[140:143], v[172:175], v[104:107]
	v_mfma_f32_16x16x32_bf16 v[92:95], v[132:135], v[180:183], v[92:95]
	v_mfma_f32_16x16x32_bf16 v[88:91], v[140:143], v[180:183], v[88:91]
	v_mfma_f32_16x16x32_bf16 v[76:79], v[132:135], v[188:191], v[76:79]
	v_mfma_f32_16x16x32_bf16 v[72:75], v[140:143], v[188:191], v[72:75]
	s_setprio 0
	s_setprio 1
	v_mfma_f32_16x16x32_bf16 v[116:119], v[144:147], v[160:163], v[116:119]
	v_mfma_f32_16x16x32_bf16 v[112:115], v[152:155], v[160:163], v[112:115]
	v_mfma_f32_16x16x32_bf16 v[100:103], v[144:147], v[168:171], v[100:103]
	v_mfma_f32_16x16x32_bf16 v[96:99], v[152:155], v[168:171], v[96:99]
	v_mfma_f32_16x16x32_bf16 v[84:87], v[144:147], v[176:179], v[84:87]
	v_mfma_f32_16x16x32_bf16 v[80:83], v[152:155], v[176:179], v[80:83]
	v_mfma_f32_16x16x32_bf16 v[68:71], v[144:147], v[184:187], v[68:71]
	v_mfma_f32_16x16x32_bf16 v[64:67], v[152:155], v[184:187], v[64:67]
	v_mfma_f32_16x16x32_bf16 v[116:119], v[148:151], v[164:167], v[116:119]
	v_mfma_f32_16x16x32_bf16 v[112:115], v[156:159], v[164:167], v[112:115]
	v_mfma_f32_16x16x32_bf16 v[100:103], v[148:151], v[172:175], v[100:103]
	v_mfma_f32_16x16x32_bf16 v[96:99], v[156:159], v[172:175], v[96:99]
	v_mfma_f32_16x16x32_bf16 v[84:87], v[148:151], v[180:183], v[84:87]
	v_mfma_f32_16x16x32_bf16 v[80:83], v[156:159], v[180:183], v[80:83]
	v_mfma_f32_16x16x32_bf16 v[68:71], v[148:151], v[188:191], v[68:71]
	v_mfma_f32_16x16x32_bf16 v[64:67], v[156:159], v[188:191], v[64:67]
	s_setprio 0
	s_barrier
; #define PG8_STAGE(bufoff, gbase, voff) do { _Pragma("unroll") for (int _i = 0; _i < 2; ++_i) \
;         __builtin_amdgcn_global_load_lds((const unsigned*)((const char*)(gbase) + (voff)[_i]), (PG8_LAS unsigned*)(lds + (bufoff) + ldsw + _i * 8192), 16, 0, 0); } while (0)
; #define PG8_LDA(dst, b, h) do { _Pragma("unroll") for (int m = 0; m < 4; ++m) _Pragma("unroll") for (int k = 0; k < 2; ++k) dst[m][k] = *(const PG8_LAS bf16x8*)(lds + PG8_SA(b, h) + aoff + m * 2048 + k * 1024); } while (0)
; #define PG8_MMA(ai, bj, At, Bt) do { __builtin_amdgcn_s_setprio(1); _Pragma("unroll") for (int m = 0; m < 4; ++m) _Pragma("unroll") for (int n = 0; n < 2; ++n) _Pragma("unroll") for (int k = 0; k < 2; ++k) \
;         acc[ai][bj][m][n] = __builtin_amdgcn_mfma_f32_16x16x32_bf16(Bt[n][k], At[m][k], acc[ai][bj][m][n], 0, 0, 0); __builtin_amdgcn_s_setprio(0); } while (0)
; #define PG8_WAIT_V(n) asm volatile("s_waitcnt vmcnt(" #n ")" ::: "memory")
; #define PG8_WAIT_L(n) asm volatile("s_waitcnt lgkmcnt(" #n ")" ::: "memory")
; template <class Epi, class Sched, bool ALIGN_EPI = false, bool SP2 = false>
; __device__ __forceinline__ void gemm_phase(PG8_LAS unsigned char* lds, const Gemm g, const Sched& S, const Epi& E) {
;     ...
;             PG8_LDA(At, 1, 1); PG8_STAGE(PG8_SB(1, 0), b3, voffB); PG8_STAGE(PG8_SB(1, 1), b3 + hstep, voffB); PG8_STAGE(PG8_SA(1, 0), a3, voffA);
;             PG8_WAIT_V(8); PG8_WAIT_L(0); PG8_BAR; PG8_MMA(1, 0, At, B0); PG8_MMA(1, 1, At, B1); PG8_BAR; PG8_SCHED;
;     __device__ __forceinline__ void operator()(const pg8::f32x4 (&acc)[2][2][4][2], const pg8::Unit& u, int wr, int wc, int fr, int fq) const {
;         const bool second = u.pm >= TOK / 256;
;         const int pm = second ? u.pm - TOK / 256 : u.pm, pn = second ? u.pn - DM / 256 : u.pn;
;         const bf16* G = second ? GB_ : GA_;
;         const int row0 = pm * 256 + wr * 64 + fr, colb = pn * 256 + wc * 32 + 8 * fq;
; #pragma unroll
;         for (int ai = 0; ai < 2; ++ai) {
;             u32x4 gv[4][2], pv[4][2];
; #pragma unroll
;             for (int m = 0; m < 4; ++m)
; #pragma unroll
;                 for (int bj = 0; bj < 2; ++bj) { const size_t off = (size_t)(row0 + ai * 128 + m * 16) * DM + colb + bj * 128;
;                     gv[m][bj] = *(const u32x4*)(G + off); pv[m][bj] = (u32x4){0u, 0u, 0u, 0u}; if (second) pv[m][bj] = *(const u32x4*)(Mg + off); }
	s_add_i32 s26, s47, s29
	v_lshl_add_u64 v[208:209], v[208:209], 0, s[6:7]
	s_mov_b32 m0, s26
	ds_read_b128 v[160:163], v226 offset:49152
	ds_read_b128 v[164:167], v226 offset:50176
	ds_read_b128 v[168:171], v226 offset:51200
	ds_read_b128 v[172:175], v226 offset:52224
	ds_read_b128 v[176:179], v226 offset:53248
	ds_read_b128 v[180:183], v226 offset:54272
	ds_read_b128 v[184:187], v226 offset:55296
	ds_read_b128 v[188:191], v226 offset:56320
	global_load_lds_dwordx4 v[208:209], off
	s_add_i32 m0, s26, 0x2000
	s_add_u32 s24, s24, 0x40080
	v_lshl_add_u64 v[208:209], v[210:211], 0, s[6:7]
	s_addc_u32 s25, s25, 0
	s_add_i32 s26, s48, s29
	global_load_lds_dwordx4 v[208:209], off
	v_lshl_add_u64 v[208:209], s[24:25], 0, v[194:195]
	s_mov_b32 m0, s26
	s_nop 0
	global_load_lds_dwordx4 v[208:209], off
	v_lshl_add_u64 v[208:209], s[24:25], 0, v[198:199]
	s_add_i32 m0, s26, 0x2000
	s_nop 0
	global_load_lds_dwordx4 v[208:209], off
	v_lshl_add_u64 v[208:209], v[212:213], 0, s[6:7]
	s_mov_b32 m0, s37
	s_nop 0
	global_load_lds_dwordx4 v[208:209], off
	v_lshl_add_u64 v[208:209], v[214:215], 0, s[6:7]
	s_mov_b32 m0, s38
	s_nop 0
	global_load_lds_dwordx4 v[208:209], off
	s_waitcnt vmcnt(8)
	s_waitcnt lgkmcnt(0)
	s_barrier
	s_setprio 1
	s_waitcnt lgkmcnt(0)
	v_mfma_f32_16x16x32_bf16 v[60:63], v[128:131], v[160:163], v[60:63]
	v_mfma_f32_16x16x32_bf16 v[56:59], v[136:139], v[160:163], v[56:59]
	v_mfma_f32_16x16x32_bf16 v[44:47], v[128:131], v[168:171], v[44:47]
	v_mfma_f32_16x16x32_bf16 v[40:43], v[136:139], v[168:171], v[40:43]
	v_mfma_f32_16x16x32_bf16 v[28:31], v[128:131], v[176:179], v[28:31]
	v_mfma_f32_16x16x32_bf16 v[24:27], v[136:139], v[176:179], v[24:27]
	v_mfma_f32_16x16x32_bf16 v[12:15], v[128:131], v[184:187], v[12:15]
	v_mfma_f32_16x16x32_bf16 v[8:11], v[136:139], v[184:187], v[8:11]
	v_mfma_f32_16x16x32_bf16 v[60:63], v[132:135], v[164:167], v[60:63]
	v_mfma_f32_16x16x32_bf16 v[56:59], v[140:143], v[164:167], v[56:59]
	v_mfma_f32_16x16x32_bf16 v[44:47], v[132:135], v[172:175], v[44:47]
	v_mfma_f32_16x16x32_bf16 v[40:43], v[140:143], v[172:175], v[40:43]
	v_mfma_f32_16x16x32_bf16 v[28:31], v[132:135], v[180:183], v[28:31]
	v_mfma_f32_16x16x32_bf16 v[24:27], v[140:143], v[180:183], v[24:27]
	v_mfma_f32_16x16x32_bf16 v[12:15], v[132:135], v[188:191], v[12:15]
	v_mfma_f32_16x16x32_bf16 v[8:11], v[140:143], v[188:191], v[8:11]
	s_setprio 0
	s_setprio 1
	v_mfma_f32_16x16x32_bf16 v[52:55], v[144:147], v[160:163], v[52:55]
	v_mfma_f32_16x16x32_bf16 v[48:51], v[152:155], v[160:163], v[48:51]
	v_mfma_f32_16x16x32_bf16 v[36:39], v[144:147], v[168:171], v[36:39]
	v_mfma_f32_16x16x32_bf16 v[32:35], v[152:155], v[168:171], v[32:35]
	v_mfma_f32_16x16x32_bf16 v[20:23], v[144:147], v[176:179], v[20:23]
	v_mfma_f32_16x16x32_bf16 v[16:19], v[152:155], v[176:179], v[16:19]
	v_mfma_f32_16x16x32_bf16 v[4:7], v[144:147], v[184:187], v[4:7]
	v_mfma_f32_16x16x32_bf16 v[0:3], v[152:155], v[184:187], v[0:3]
	v_mfma_f32_16x16x32_bf16 v[52:55], v[148:151], v[164:167], v[52:55]
	v_mfma_f32_16x16x32_bf16 v[48:51], v[156:159], v[164:167], v[48:51]
	v_mfma_f32_16x16x32_bf16 v[36:39], v[148:151], v[172:175], v[36:39]
	v_mfma_f32_16x16x32_bf16 v[32:35], v[156:159], v[172:175], v[32:35]
	v_mfma_f32_16x16x32_bf16 v[20:23], v[148:151], v[180:183], v[20:23]
	v_mfma_f32_16x16x32_bf16 v[16:19], v[156:159], v[180:183], v[16:19]
	v_mfma_f32_16x16x32_bf16 v[4:7], v[148:151], v[188:191], v[4:7]
	v_mfma_f32_16x16x32_bf16 v[0:3], v[156:159], v[188:191], v[0:3]
	s_setprio 0
	s_barrier
	s_mov_b32 s100, 0
	s_add_i32 s46, s46, 2
	s_add_u32 s0, s0, 0x100
	s_addc_u32 s1, s1, 0
	s_add_u32 s44, s44, 0x100
	s_addc_u32 s45, s45, 0
	s_cmp_gt_u32 s46, 13
	s_cbranch_scc0 .LBB0_884
	s_and_b64 vcc, exec, s[8:9]
	s_cbranch_vccz .LBB0_887
	s_barrier
.LBB0_887:
	s_add_u32 s98, s23, 0x40080
	s_addc_u32 s99, s15, 0
	v_lshl_add_u64 v[252:253], s[98:99], 0, v[200:201]
	s_add_i32 m0, s21, 0xc000
	s_nop 0
	global_load_lds_dwordx4 v[252:253], off
	v_lshl_add_u64 v[252:253], s[98:99], 0, v[202:203]
	s_add_i32 m0, s21, 0xe000
	s_nop 0
	global_load_lds_dwordx4 v[252:253], off
	s_mov_b32 s100, 1
	s_lshl_b32 s13, s20, 8
	s_lshl_b32 s26, s22, 8
	s_add_i32 s15, s13, 0xffffc000
	s_add_i32 s27, s26, 0xfffff800
	s_cmp_gt_i32 s20, 63
	s_cselect_b64 s[24:25], -1, 0
	s_and_b64 s[0:1], s[24:25], exec
	s_cselect_b32 s0, s15, s13
	s_cselect_b32 s1, s27, s26
	v_add_u32_e32 v210, s0, v221
	v_or_b32_e32 v208, s1, v223
	v_ashrrev_i32_e32 v211, 31, v210
	v_ashrrev_i32_e32 v209, 31, v208
	v_lshlrev_b64 v[128:129], 11, v[210:211]
	s_cselect_b32 s22, s35, s76
	s_cselect_b32 s23, s36, s50
	v_lshl_add_u64 v[128:129], v[128:129], 0, v[208:209]
	v_lshl_add_u64 v[130:131], v[128:129], 1, s[22:23]
	global_load_dwordx4 v[188:191], v[130:131], off
	s_cmp_lt_i32 s20, 64
	v_mov_b32_e32 v168, 0
	v_lshl_add_u64 v[128:129], v[128:129], 1, s[84:85]
	v_mov_b32_e32 v184, 0
	v_mov_b32_e32 v185, 0
	v_mov_b32_e32 v186, 0
	v_mov_b32_e32 v187, 0
	s_cbranch_scc1 .LBB0_889
	global_load_dwordx4 v[184:187], v[128:129], off
